# gemm_in: RoPE tiles (latent rows, q_a/k_a columns) get a straight-line epilogue: rope-table loads in two batches of 16, in-place rotation, packed stores
# speedup vs baseline: 1.0091x; 1.0091x over previous
.Lgin_cls_lat:
	s_cmp_lt_u32 s16, 6
	s_cbranch_scc1 .Lgin_rvar
	s_sub_u32 s4, s16, 8
	s_cmp_lt_u32 s4, 32
	s_cbranch_scc1 .Lgin_plain
	s_sub_u32 s4, s16, 45
	s_cmp_lt_u32 s4, 3
	s_cbranch_scc1 .Lgin_plain
	s_sub_u32 s4, s16, 6
	s_cmp_lt_u32 s4, 2
	s_cbranch_scc1 .Lgin_vvar
	s_sub_u32 s4, s16, 41
	s_cmp_lt_u32 s4, 3
	s_cbranch_scc1 .Lgin_vvar
	s_branch .Lgin_notplain

.Lgin_rvar:
	s_mul_i32 s6, s0, 0x3020
	s_lshl_b32 s7, s16, 8
	v_readlane_b32 s4, v254, 4
	v_readlane_b32 s5, v254, 5
	v_add_u32_e32 v128, v174, v166
	v_add_u32_e32 v129, v173, v179
	v_mul_u32_u24_e32 v128, 0x3020, v128
	s_add_u32 s6, s6, s7
	v_lshl_add_u32 v128, v129, 1, v128
	s_add_u32 s4, s4, s6
	s_addc_u32 s5, s5, 0
	v_readlane_b32 s10, v254, 41
	v_readlane_b32 s11, v254, 42
	s_sub_u32 s6, s0, 0x2000
	s_and_b32 s6, s6, 0x3ff
	v_add_u32_e32 v130, v174, v166
	v_add_u32_e32 v130, s6, v130
	v_lshlrev_b32_e32 v130, 9, v130
	v_lshl_add_u32 v130, v173, 2, v130
	v_lshl_add_u32 v130, v179, 3, v130
	global_load_dwordx4 v[230:233], v130, s[10:11]
	global_load_dwordx4 v[234:237], v130, s[10:11] offset:16
	global_load_dwordx4 v[238:241], v130, s[10:11] offset:128
	global_load_dwordx4 v[242:245], v130, s[10:11] offset:144
	s_add_u32 s10, s10, 0x2000
	s_addc_u32 s11, s11, 0
	global_load_dwordx4 v[136:139], v130, s[10:11]
	global_load_dwordx4 v[140:143], v130, s[10:11] offset:16
	global_load_dwordx4 v[144:147], v130, s[10:11] offset:128
	global_load_dwordx4 v[148:151], v130, s[10:11] offset:144
	s_add_u32 s10, s10, 0x2000
	s_addc_u32 s11, s11, 0
	global_load_dwordx4 v[182:185], v130, s[10:11]
	global_load_dwordx4 v[186:189], v130, s[10:11] offset:16
	global_load_dwordx4 v[190:193], v130, s[10:11] offset:128
	global_load_dwordx4 v[194:197], v130, s[10:11] offset:144
	s_add_u32 s10, s10, 0x2000
	s_addc_u32 s11, s11, 0
	global_load_dwordx4 v[198:201], v130, s[10:11]
	global_load_dwordx4 v[202:205], v130, s[10:11] offset:16
	global_load_dwordx4 v[222:225], v130, s[10:11] offset:128
	global_load_dwordx4 v[226:229], v130, s[10:11] offset:144
	s_add_u32 s10, s10, 0x2000
	s_addc_u32 s11, s11, 0
	s_waitcnt vmcnt(14)
	v_mul_f32_e32 v152, v60, v231
	v_mul_f32_e32 v153, v124, v231
	v_fma_f32 v124, v124, v230, -v152
	v_fma_f32 v60, v60, v230, v153
	v_mul_f32_e32 v154, v61, v233
	v_mul_f32_e32 v155, v125, v233
	v_fma_f32 v125, v125, v232, -v154
	v_fma_f32 v61, v61, v232, v155
	v_mul_f32_e32 v152, v62, v235
	v_mul_f32_e32 v153, v126, v235
	v_fma_f32 v126, v126, v234, -v152
	v_fma_f32 v62, v62, v234, v153
	v_mul_f32_e32 v154, v63, v237
	v_mul_f32_e32 v155, v127, v237
	v_fma_f32 v127, v127, v236, -v154
	v_fma_f32 v63, v63, v236, v155
	s_waitcnt vmcnt(12)
	v_mul_f32_e32 v152, v28, v239
	v_mul_f32_e32 v153, v92, v239
	v_fma_f32 v92, v92, v238, -v152
	v_fma_f32 v28, v28, v238, v153
	v_mul_f32_e32 v154, v29, v241
	v_mul_f32_e32 v155, v93, v241
	v_fma_f32 v93, v93, v240, -v154
	v_fma_f32 v29, v29, v240, v155
	v_mul_f32_e32 v152, v30, v243
	v_mul_f32_e32 v153, v94, v243
	v_fma_f32 v94, v94, v242, -v152
	v_fma_f32 v30, v30, v242, v153
	v_mul_f32_e32 v154, v31, v245
	v_mul_f32_e32 v155, v95, v245
	v_fma_f32 v95, v95, v244, -v154
	v_fma_f32 v31, v31, v244, v155
	s_waitcnt vmcnt(10)
	v_mul_f32_e32 v152, v56, v137
	v_mul_f32_e32 v153, v120, v137
	v_fma_f32 v120, v120, v136, -v152
	v_fma_f32 v56, v56, v136, v153
	v_mul_f32_e32 v154, v57, v139
	v_mul_f32_e32 v155, v121, v139
	v_fma_f32 v121, v121, v138, -v154
	v_fma_f32 v57, v57, v138, v155
	v_mul_f32_e32 v152, v58, v141
	v_mul_f32_e32 v153, v122, v141
	v_fma_f32 v122, v122, v140, -v152
	v_fma_f32 v58, v58, v140, v153
	v_mul_f32_e32 v154, v59, v143
	v_mul_f32_e32 v155, v123, v143
	v_fma_f32 v123, v123, v142, -v154
	v_fma_f32 v59, v59, v142, v155
	s_waitcnt vmcnt(8)
	v_mul_f32_e32 v152, v24, v145
	v_mul_f32_e32 v153, v88, v145
	v_fma_f32 v88, v88, v144, -v152
	v_fma_f32 v24, v24, v144, v153
	v_mul_f32_e32 v154, v25, v147
	v_mul_f32_e32 v155, v89, v147
	v_fma_f32 v89, v89, v146, -v154
	v_fma_f32 v25, v25, v146, v155
	v_mul_f32_e32 v152, v26, v149
	v_mul_f32_e32 v153, v90, v149
	v_fma_f32 v90, v90, v148, -v152
	v_fma_f32 v26, v26, v148, v153
	v_mul_f32_e32 v154, v27, v151
	v_mul_f32_e32 v155, v91, v151
	v_fma_f32 v91, v91, v150, -v154
	v_fma_f32 v27, v27, v150, v155
	s_waitcnt vmcnt(6)
	v_mul_f32_e32 v152, v52, v183
	v_mul_f32_e32 v153, v116, v183
	v_fma_f32 v116, v116, v182, -v152
	v_fma_f32 v52, v52, v182, v153
	v_mul_f32_e32 v154, v53, v185
	v_mul_f32_e32 v155, v117, v185
	v_fma_f32 v117, v117, v184, -v154
	v_fma_f32 v53, v53, v184, v155
	v_mul_f32_e32 v152, v54, v187
	v_mul_f32_e32 v153, v118, v187
	v_fma_f32 v118, v118, v186, -v152
	v_fma_f32 v54, v54, v186, v153
	v_mul_f32_e32 v154, v55, v189
	v_mul_f32_e32 v155, v119, v189
	v_fma_f32 v119, v119, v188, -v154
	v_fma_f32 v55, v55, v188, v155
	s_waitcnt vmcnt(4)
	v_mul_f32_e32 v152, v20, v191
	v_mul_f32_e32 v153, v84, v191
	v_fma_f32 v84, v84, v190, -v152
	v_fma_f32 v20, v20, v190, v153
	v_mul_f32_e32 v154, v21, v193
	v_mul_f32_e32 v155, v85, v193
	v_fma_f32 v85, v85, v192, -v154
	v_fma_f32 v21, v21, v192, v155
	v_mul_f32_e32 v152, v22, v195
	v_mul_f32_e32 v153, v86, v195
	v_fma_f32 v86, v86, v194, -v152
	v_fma_f32 v22, v22, v194, v153
	v_mul_f32_e32 v154, v23, v197
	v_mul_f32_e32 v155, v87, v197
	v_fma_f32 v87, v87, v196, -v154
	v_fma_f32 v23, v23, v196, v155
	s_waitcnt vmcnt(2)
	v_mul_f32_e32 v152, v48, v199
	v_mul_f32_e32 v153, v112, v199
	v_fma_f32 v112, v112, v198, -v152
	v_fma_f32 v48, v48, v198, v153
	v_mul_f32_e32 v154, v49, v201
	v_mul_f32_e32 v155, v113, v201
	v_fma_f32 v113, v113, v200, -v154
	v_fma_f32 v49, v49, v200, v155
	v_mul_f32_e32 v152, v50, v203
	v_mul_f32_e32 v153, v114, v203
	v_fma_f32 v114, v114, v202, -v152
	v_fma_f32 v50, v50, v202, v153
	v_mul_f32_e32 v154, v51, v205
	v_mul_f32_e32 v155, v115, v205
	v_fma_f32 v115, v115, v204, -v154
	v_fma_f32 v51, v51, v204, v155
	s_waitcnt vmcnt(0)
	v_mul_f32_e32 v152, v16, v223
	v_mul_f32_e32 v153, v80, v223
	v_fma_f32 v80, v80, v222, -v152
	v_fma_f32 v16, v16, v222, v153
	v_mul_f32_e32 v154, v17, v225
	v_mul_f32_e32 v155, v81, v225
	v_fma_f32 v81, v81, v224, -v154
	v_fma_f32 v17, v17, v224, v155
	v_mul_f32_e32 v152, v18, v227
	v_mul_f32_e32 v153, v82, v227
	v_fma_f32 v82, v82, v226, -v152
	v_fma_f32 v18, v18, v226, v153
	v_mul_f32_e32 v154, v19, v229
	v_mul_f32_e32 v155, v83, v229
	v_fma_f32 v83, v83, v228, -v154
	v_fma_f32 v19, v19, v228, v155
	global_load_dwordx4 v[230:233], v130, s[10:11]
	global_load_dwordx4 v[234:237], v130, s[10:11] offset:16
	global_load_dwordx4 v[238:241], v130, s[10:11] offset:128
	global_load_dwordx4 v[242:245], v130, s[10:11] offset:144
	s_add_u32 s10, s10, 0x2000
	s_addc_u32 s11, s11, 0
	global_load_dwordx4 v[136:139], v130, s[10:11]
	global_load_dwordx4 v[140:143], v130, s[10:11] offset:16
	global_load_dwordx4 v[144:147], v130, s[10:11] offset:128
	global_load_dwordx4 v[148:151], v130, s[10:11] offset:144
	s_add_u32 s10, s10, 0x2000
	s_addc_u32 s11, s11, 0
	global_load_dwordx4 v[182:185], v130, s[10:11]
	global_load_dwordx4 v[186:189], v130, s[10:11] offset:16
	global_load_dwordx4 v[190:193], v130, s[10:11] offset:128
	global_load_dwordx4 v[194:197], v130, s[10:11] offset:144
	s_add_u32 s10, s10, 0x2000
	s_addc_u32 s11, s11, 0
	global_load_dwordx4 v[198:201], v130, s[10:11]
	global_load_dwordx4 v[202:205], v130, s[10:11] offset:16
	global_load_dwordx4 v[222:225], v130, s[10:11] offset:128
	global_load_dwordx4 v[226:229], v130, s[10:11] offset:144
	s_add_u32 s10, s10, 0x2000
	s_addc_u32 s11, s11, 0
	v_cvt_pk_f16_f32 v124, v124, v125
	v_cvt_pk_f16_f32 v125, v126, v127
	global_store_dwordx2 v128, v[124:125], s[4:5]
	v_cvt_pk_f16_f32 v92, v92, v93
	v_cvt_pk_f16_f32 v93, v94, v95
	global_store_dwordx2 v128, v[92:93], s[4:5] offset:32
	v_cvt_pk_f16_f32 v60, v60, v61
	v_cvt_pk_f16_f32 v61, v62, v63
	global_store_dwordx2 v128, v[60:61], s[4:5] offset:64
	v_cvt_pk_f16_f32 v28, v28, v29
	v_cvt_pk_f16_f32 v29, v30, v31
	global_store_dwordx2 v128, v[28:29], s[4:5] offset:96
	s_add_u32 s4, s4, 0x30200
	s_addc_u32 s5, s5, 0
	v_cvt_pk_f16_f32 v120, v120, v121
	v_cvt_pk_f16_f32 v121, v122, v123
	global_store_dwordx2 v128, v[120:121], s[4:5]
	v_cvt_pk_f16_f32 v88, v88, v89
	v_cvt_pk_f16_f32 v89, v90, v91
	global_store_dwordx2 v128, v[88:89], s[4:5] offset:32
	v_cvt_pk_f16_f32 v56, v56, v57
	v_cvt_pk_f16_f32 v57, v58, v59
	global_store_dwordx2 v128, v[56:57], s[4:5] offset:64
	v_cvt_pk_f16_f32 v24, v24, v25
	v_cvt_pk_f16_f32 v25, v26, v27
	global_store_dwordx2 v128, v[24:25], s[4:5] offset:96
	s_add_u32 s4, s4, 0x30200
	s_addc_u32 s5, s5, 0
	v_cvt_pk_f16_f32 v116, v116, v117
	v_cvt_pk_f16_f32 v117, v118, v119
	global_store_dwordx2 v128, v[116:117], s[4:5]
	v_cvt_pk_f16_f32 v84, v84, v85
	v_cvt_pk_f16_f32 v85, v86, v87
	global_store_dwordx2 v128, v[84:85], s[4:5] offset:32
	v_cvt_pk_f16_f32 v52, v52, v53
	v_cvt_pk_f16_f32 v53, v54, v55
	global_store_dwordx2 v128, v[52:53], s[4:5] offset:64
	v_cvt_pk_f16_f32 v20, v20, v21
	v_cvt_pk_f16_f32 v21, v22, v23
	global_store_dwordx2 v128, v[20:21], s[4:5] offset:96
	s_add_u32 s4, s4, 0x30200
	s_addc_u32 s5, s5, 0
	v_cvt_pk_f16_f32 v112, v112, v113
	v_cvt_pk_f16_f32 v113, v114, v115
	global_store_dwordx2 v128, v[112:113], s[4:5]
	v_cvt_pk_f16_f32 v80, v80, v81
	v_cvt_pk_f16_f32 v81, v82, v83
	global_store_dwordx2 v128, v[80:81], s[4:5] offset:32
	v_cvt_pk_f16_f32 v48, v48, v49
	v_cvt_pk_f16_f32 v49, v50, v51
	global_store_dwordx2 v128, v[48:49], s[4:5] offset:64
	v_cvt_pk_f16_f32 v16, v16, v17
	v_cvt_pk_f16_f32 v17, v18, v19
	global_store_dwordx2 v128, v[16:17], s[4:5] offset:96
	s_add_u32 s4, s4, 0x30200
	s_addc_u32 s5, s5, 0
	s_waitcnt vmcnt(30)
	v_mul_f32_e32 v152, v44, v231
	v_mul_f32_e32 v153, v108, v231
	v_fma_f32 v108, v108, v230, -v152
	v_fma_f32 v44, v44, v230, v153
	v_mul_f32_e32 v154, v45, v233
	v_mul_f32_e32 v155, v109, v233
	v_fma_f32 v109, v109, v232, -v154
	v_fma_f32 v45, v45, v232, v155
	v_mul_f32_e32 v152, v46, v235
	v_mul_f32_e32 v153, v110, v235
	v_fma_f32 v110, v110, v234, -v152
	v_fma_f32 v46, v46, v234, v153
	v_mul_f32_e32 v154, v47, v237
	v_mul_f32_e32 v155, v111, v237
	v_fma_f32 v111, v111, v236, -v154
	v_fma_f32 v47, v47, v236, v155
	s_waitcnt vmcnt(28)
	v_mul_f32_e32 v152, v12, v239
	v_mul_f32_e32 v153, v76, v239
	v_fma_f32 v76, v76, v238, -v152
	v_fma_f32 v12, v12, v238, v153
	v_mul_f32_e32 v154, v13, v241
	v_mul_f32_e32 v155, v77, v241
	v_fma_f32 v77, v77, v240, -v154
	v_fma_f32 v13, v13, v240, v155
	v_mul_f32_e32 v152, v14, v243
	v_mul_f32_e32 v153, v78, v243
	v_fma_f32 v78, v78, v242, -v152
	v_fma_f32 v14, v14, v242, v153
	v_mul_f32_e32 v154, v15, v245
	v_mul_f32_e32 v155, v79, v245
	v_fma_f32 v79, v79, v244, -v154
	v_fma_f32 v15, v15, v244, v155
	s_waitcnt vmcnt(26)
	v_mul_f32_e32 v152, v40, v137
	v_mul_f32_e32 v153, v104, v137
	v_fma_f32 v104, v104, v136, -v152
	v_fma_f32 v40, v40, v136, v153
	v_mul_f32_e32 v154, v41, v139
	v_mul_f32_e32 v155, v105, v139
	v_fma_f32 v105, v105, v138, -v154
	v_fma_f32 v41, v41, v138, v155
	v_mul_f32_e32 v152, v42, v141
	v_mul_f32_e32 v153, v106, v141
	v_fma_f32 v106, v106, v140, -v152
	v_fma_f32 v42, v42, v140, v153
	v_mul_f32_e32 v154, v43, v143
	v_mul_f32_e32 v155, v107, v143
	v_fma_f32 v107, v107, v142, -v154
	v_fma_f32 v43, v43, v142, v155
	s_waitcnt vmcnt(24)
	v_mul_f32_e32 v152, v8, v145
	v_mul_f32_e32 v153, v72, v145
	v_fma_f32 v72, v72, v144, -v152
	v_fma_f32 v8, v8, v144, v153
	v_mul_f32_e32 v154, v9, v147
	v_mul_f32_e32 v155, v73, v147
	v_fma_f32 v73, v73, v146, -v154
	v_fma_f32 v9, v9, v146, v155
	v_mul_f32_e32 v152, v10, v149
	v_mul_f32_e32 v153, v74, v149
	v_fma_f32 v74, v74, v148, -v152
	v_fma_f32 v10, v10, v148, v153
	v_mul_f32_e32 v154, v11, v151
	v_mul_f32_e32 v155, v75, v151
	v_fma_f32 v75, v75, v150, -v154
	v_fma_f32 v11, v11, v150, v155
	s_waitcnt vmcnt(22)
	v_mul_f32_e32 v152, v36, v183
	v_mul_f32_e32 v153, v100, v183
	v_fma_f32 v100, v100, v182, -v152
	v_fma_f32 v36, v36, v182, v153
	v_mul_f32_e32 v154, v37, v185
	v_mul_f32_e32 v155, v101, v185
	v_fma_f32 v101, v101, v184, -v154
	v_fma_f32 v37, v37, v184, v155
	v_mul_f32_e32 v152, v38, v187
	v_mul_f32_e32 v153, v102, v187
	v_fma_f32 v102, v102, v186, -v152
	v_fma_f32 v38, v38, v186, v153
	v_mul_f32_e32 v154, v39, v189
	v_mul_f32_e32 v155, v103, v189
	v_fma_f32 v103, v103, v188, -v154
	v_fma_f32 v39, v39, v188, v155
	s_waitcnt vmcnt(20)
	v_mul_f32_e32 v152, v4, v191
	v_mul_f32_e32 v153, v68, v191
	v_fma_f32 v68, v68, v190, -v152
	v_fma_f32 v4, v4, v190, v153
	v_mul_f32_e32 v154, v5, v193
	v_mul_f32_e32 v155, v69, v193
	v_fma_f32 v69, v69, v192, -v154
	v_fma_f32 v5, v5, v192, v155
	v_mul_f32_e32 v152, v6, v195
	v_mul_f32_e32 v153, v70, v195
	v_fma_f32 v70, v70, v194, -v152
	v_fma_f32 v6, v6, v194, v153
	v_mul_f32_e32 v154, v7, v197
	v_mul_f32_e32 v155, v71, v197
	v_fma_f32 v71, v71, v196, -v154
	v_fma_f32 v7, v7, v196, v155
	s_waitcnt vmcnt(18)
	v_mul_f32_e32 v152, v32, v199
	v_mul_f32_e32 v153, v96, v199
	v_fma_f32 v96, v96, v198, -v152
	v_fma_f32 v32, v32, v198, v153
	v_mul_f32_e32 v154, v33, v201
	v_mul_f32_e32 v155, v97, v201
	v_fma_f32 v97, v97, v200, -v154
	v_fma_f32 v33, v33, v200, v155
	v_mul_f32_e32 v152, v34, v203
	v_mul_f32_e32 v153, v98, v203
	v_fma_f32 v98, v98, v202, -v152
	v_fma_f32 v34, v34, v202, v153
	v_mul_f32_e32 v154, v35, v205
	v_mul_f32_e32 v155, v99, v205
	v_fma_f32 v99, v99, v204, -v154
	v_fma_f32 v35, v35, v204, v155
	s_waitcnt vmcnt(16)
	v_mul_f32_e32 v152, v0, v223
	v_mul_f32_e32 v153, v64, v223
	v_fma_f32 v64, v64, v222, -v152
	v_fma_f32 v0, v0, v222, v153
	v_mul_f32_e32 v154, v1, v225
	v_mul_f32_e32 v155, v65, v225
	v_fma_f32 v65, v65, v224, -v154
	v_fma_f32 v1, v1, v224, v155
	v_mul_f32_e32 v152, v2, v227
	v_mul_f32_e32 v153, v66, v227
	v_fma_f32 v66, v66, v226, -v152
	v_fma_f32 v2, v2, v226, v153
	v_mul_f32_e32 v154, v3, v229
	v_mul_f32_e32 v155, v67, v229
	v_fma_f32 v67, v67, v228, -v154
	v_fma_f32 v3, v3, v228, v155
	v_cvt_pk_f16_f32 v108, v108, v109
	v_cvt_pk_f16_f32 v109, v110, v111
	global_store_dwordx2 v128, v[108:109], s[4:5]
	v_cvt_pk_f16_f32 v76, v76, v77
	v_cvt_pk_f16_f32 v77, v78, v79
	global_store_dwordx2 v128, v[76:77], s[4:5] offset:32
	v_cvt_pk_f16_f32 v44, v44, v45
	v_cvt_pk_f16_f32 v45, v46, v47
	global_store_dwordx2 v128, v[44:45], s[4:5] offset:64
	v_cvt_pk_f16_f32 v12, v12, v13
	v_cvt_pk_f16_f32 v13, v14, v15
	global_store_dwordx2 v128, v[12:13], s[4:5] offset:96
	s_add_u32 s4, s4, 0x30200
	s_addc_u32 s5, s5, 0
	v_cvt_pk_f16_f32 v104, v104, v105
	v_cvt_pk_f16_f32 v105, v106, v107
	global_store_dwordx2 v128, v[104:105], s[4:5]
	v_cvt_pk_f16_f32 v72, v72, v73
	v_cvt_pk_f16_f32 v73, v74, v75
	global_store_dwordx2 v128, v[72:73], s[4:5] offset:32
	v_cvt_pk_f16_f32 v40, v40, v41
	v_cvt_pk_f16_f32 v41, v42, v43
	global_store_dwordx2 v128, v[40:41], s[4:5] offset:64
	v_cvt_pk_f16_f32 v8, v8, v9
	v_cvt_pk_f16_f32 v9, v10, v11
	global_store_dwordx2 v128, v[8:9], s[4:5] offset:96
	s_add_u32 s4, s4, 0x30200
	s_addc_u32 s5, s5, 0
	v_cvt_pk_f16_f32 v100, v100, v101
	v_cvt_pk_f16_f32 v101, v102, v103
	global_store_dwordx2 v128, v[100:101], s[4:5]
	v_cvt_pk_f16_f32 v68, v68, v69
	v_cvt_pk_f16_f32 v69, v70, v71
	global_store_dwordx2 v128, v[68:69], s[4:5] offset:32
	v_cvt_pk_f16_f32 v36, v36, v37
	v_cvt_pk_f16_f32 v37, v38, v39
	global_store_dwordx2 v128, v[36:37], s[4:5] offset:64
	v_cvt_pk_f16_f32 v4, v4, v5
	v_cvt_pk_f16_f32 v5, v6, v7
	global_store_dwordx2 v128, v[4:5], s[4:5] offset:96
	s_add_u32 s4, s4, 0x30200
	s_addc_u32 s5, s5, 0
	v_cvt_pk_f16_f32 v96, v96, v97
	v_cvt_pk_f16_f32 v97, v98, v99
	global_store_dwordx2 v128, v[96:97], s[4:5]
	v_cvt_pk_f16_f32 v64, v64, v65
	v_cvt_pk_f16_f32 v65, v66, v67
	global_store_dwordx2 v128, v[64:65], s[4:5] offset:32
	v_cvt_pk_f16_f32 v32, v32, v33
	v_cvt_pk_f16_f32 v33, v34, v35
	global_store_dwordx2 v128, v[32:33], s[4:5] offset:64
	v_cvt_pk_f16_f32 v0, v0, v1
	v_cvt_pk_f16_f32 v1, v2, v3
	global_store_dwordx2 v128, v[0:1], s[4:5] offset:96
	s_mov_b64 s[50:51], exec
	s_branch .LBB0_315
